# P10 stage-2 (product-key candidates) selection also uses threshold rounds
# baseline (speedup 1.0000x reference)
; DI void peer_topk_wave(const Params& p, int item, unsigned* lds  ) {
;     ...
;   unsigned cand[13];
;     ...
;   CAND(0, 0, 0, 0, 13, 2, 0, 6, 1)
;   CAND(1, 0, 1, 0, 14, 2, 1, 7, 0)
;   CAND(2, 0, 2, 0, 15, 2, 2, 7, 1)
;   CAND(3, 0, 3, 1, 0, 2, 3, 8, 0)
;   CAND(4, 0, 4, 1, 1, 2, 4, 9, 0)
;   CAND(5, 0, 5, 1, 2, 3, 0, 10, 0)
;   CAND(6, 0, 6, 1, 3, 3, 1, 11, 0)
;   CAND(7, 0, 7, 1, 4, 3, 2, 12, 0)
;   CAND(8, 0, 8, 1, 5, 3, 3, 13, 0)
;   CAND(9, 0, 9, 1, 6, 4, 2, 14, 0)
;   CAND(10, 0, 10, 1, 7, 5, 0, 15, 0)
;   CAND(11, 0, 11, 4, 0, 5, 1, -1, -1)
;   CAND(12, 0, 12, 4, 1, 6, 0, -1, -1)
;     ...
;   unsigned w2[16];
; #pragma unroll
;   for (int rr = 0; rr < 16; ++rr) {
;     unsigned m = 0;
; #pragma unroll
;     for (int i = 0; i < 13; ++i) m = umax(m, cand[i]);
;     m = umax(m, (unsigned)__shfl_xor((int)m, 16));
;     m = umax(m, (unsigned)__shfl_xor((int)m, 32));
;     w2[rr] = m;
; #pragma unroll
;     for (int i = 0; i < 13; ++i) cand[i] = (cand[i] == m) ? 0u : cand[i];
;   }
.LBB0_1279:
	s_or_b64 exec, exec, s[0:1]
	v_add_f32_e32 v164, v197, v198
	v_not_b32_e32 v197, v164
	v_or_b32_e32 v198, 0x80000000, v164
	v_cmp_gt_i32_e32 vcc, 0, v164
	v_add_f32_e32 v162, v162, v183
	v_not_b32_e32 v183, v162
	v_cndmask_b32_e32 v164, v198, v197, vcc
	v_or_b32_e32 v197, 0x80000000, v162
	v_cmp_gt_i32_e32 vcc, 0, v162
	v_add_f32_e32 v187, v187, v188
	v_not_b32_e32 v188, v187
	v_cndmask_b32_e32 v162, v197, v183, vcc
	v_add_f32_e32 v183, v193, v194
	v_not_b32_e32 v193, v183
	v_or_b32_e32 v194, 0x80000000, v183
	v_cmp_gt_i32_e32 vcc, 0, v183
	v_add_f32_e32 v184, v184, v185
	v_not_b32_e32 v185, v184
	v_cndmask_b32_e32 v183, v194, v193, vcc
	v_and_or_b32 v182, v183, s82, v182
	v_add_f32_e32 v183, v190, v192
	v_not_b32_e32 v190, v183
	v_or_b32_e32 v192, 0x80000000, v183
	v_cmp_gt_i32_e32 vcc, 0, v183
	v_add_f32_e32 v179, v179, v180
	v_not_b32_e32 v180, v179
	v_cndmask_b32_e32 v183, v192, v190, vcc
	v_or_b32_e32 v190, 0x80000000, v187
	v_cmp_gt_i32_e32 vcc, 0, v187
	v_add_f32_e32 v176, v176, v177
	v_not_b32_e32 v177, v176
	v_cndmask_b32_e32 v187, v190, v188, vcc
	v_or_b32_e32 v188, 0x80000000, v184
	v_cmp_gt_i32_e32 vcc, 0, v184
	v_add_f32_e32 v171, v171, v172
	v_not_b32_e32 v172, v171
	v_cndmask_b32_e32 v184, v188, v185, vcc
	v_or_b32_e32 v185, 0x80000000, v179
	v_cmp_gt_i32_e32 vcc, 0, v179
	v_and_or_b32 v184, v184, s82, v186
	v_and_or_b32 v183, v183, s82, v191
	v_cndmask_b32_e32 v179, v185, v180, vcc
	v_or_b32_e32 v180, 0x80000000, v176
	v_cmp_gt_i32_e32 vcc, 0, v176
	v_and_or_b32 v179, v179, s82, v181
	v_and_or_b32 v187, v187, s82, v189
	v_cndmask_b32_e32 v176, v180, v177, vcc
	v_or_b32_e32 v177, 0x80000000, v171
	v_cmp_gt_i32_e32 vcc, 0, v171
	v_and_or_b32 v176, v176, s82, v178
	v_and_or_b32 v164, v164, s82, v201
	v_cndmask_b32_e32 v171, v177, v172, vcc
	v_and_or_b32 v171, v171, s82, v173
	v_and_b32_e32 v172, 0x7fffff80, v153
	v_bitop3_b32 v173, v153, s81, v153 bitop3:0xcf
	v_cmp_gt_i32_e32 vcc, 0, v153
	v_and_or_b32 v162, v162, s82, v195
	v_cndmask_b32_e64 v164, v164, 0, s[12:13]
	v_cndmask_b32_e32 v172, v173, v172, vcc
	v_cndmask_b32_e64 v172, v172, v169, s[10:11]
	v_cndmask_b32_e64 v172, v172, v168, s[4:5]
	v_add_f32_e32 v166, v172, v166
	v_not_b32_e32 v173, v166
	v_or_b32_e32 v177, 0x80000000, v166
	v_cmp_gt_i32_e32 vcc, 0, v166
	v_add_f32_e32 v88, v172, v88
	v_or_b32_e32 v172, 0x80000000, v88
	v_cndmask_b32_e32 v166, v177, v173, vcc
	v_and_or_b32 v167, v166, s82, v167
	v_not_b32_e32 v166, v88
	v_cmp_gt_i32_e32 vcc, 0, v88
	s_nop 1
	v_cndmask_b32_e32 v88, v172, v166, vcc
	v_and_or_b32 v88, v88, s82, v165
	v_cndmask_b32_e64 v165, v200, v169, s[10:11]
	v_cndmask_b32_e64 v165, v165, v168, s[4:5]
	v_add_f32_e32 v86, v165, v86
	v_not_b32_e32 v165, v86
	v_or_b32_e32 v166, 0x80000000, v86
	v_cmp_gt_i32_e32 vcc, 0, v86
	s_nop 1
	v_cndmask_b32_e32 v86, v166, v165, vcc
	v_and_or_b32 v86, v86, s82, v87
	v_add_f32_e32 v87, v199, v196
	v_not_b32_e32 v165, v87
	v_or_b32_e32 v166, 0x80000000, v87
	v_cmp_gt_i32_e32 vcc, 0, v87
	s_nop 1
	v_cndmask_b32_e32 v87, v166, v165, vcc
	v_and_or_b32 v87, v87, s82, v89
	v_cndmask_b32_e64 v87, v87, 0, s[12:13]
	s_nop 1
	v_max3_u32 v24, v86, v88, v167
	v_max3_u32 v24, v24, v171, v176
	v_max3_u32 v24, v24, v179, v184
	v_max3_u32 v24, v24, v187, v183
	v_max3_u32 v24, v24, v182, v162
	v_max3_u32 v24, v24, v164, v87
	v_mov_b32_e32 v25, v24
	s_nop 1
	v_permlane16_swap_b32 v24, v25
	s_nop 1
	v_max_u32_e32 v24, v24, v25
	v_mov_b32_e32 v25, v24
	s_nop 1
	v_permlane32_swap_b32 v24, v25
	s_nop 1
	v_max_u32_e32 v40, v24, v25
	v_sub_u32_e32 v26, v86, v40
	v_sub_u32_e32 v27, v88, v40
	v_sub_u32_e32 v28, v167, v40
	v_max3_u32 v24, v26, v27, v28
	v_sub_u32_e32 v29, v171, v40
	v_sub_u32_e32 v30, v176, v40
	v_max3_u32 v24, v24, v29, v30
	v_sub_u32_e32 v31, v179, v40
	v_sub_u32_e32 v32, v184, v40
	v_max3_u32 v24, v24, v31, v32
	v_sub_u32_e32 v33, v187, v40
	v_sub_u32_e32 v26, v183, v40
	v_max3_u32 v24, v24, v33, v26
	v_sub_u32_e32 v27, v182, v40
	v_sub_u32_e32 v28, v162, v40
	v_max3_u32 v24, v24, v27, v28
	v_sub_u32_e32 v29, v164, v40
	v_sub_u32_e32 v30, v87, v40
	v_max3_u32 v24, v24, v29, v30
	v_mov_b32_e32 v25, v24
	s_nop 1
	v_permlane16_swap_b32 v24, v25
	s_nop 1
	v_max_u32_e32 v24, v24, v25
	v_mov_b32_e32 v25, v24
	s_nop 1
	v_permlane32_swap_b32 v24, v25
	s_nop 1
	v_max_u32_e32 v24, v24, v25
	v_add_u32_e32 v41, v24, v40
	v_sub_u32_e32 v26, v86, v41
	v_sub_u32_e32 v27, v88, v41
	v_sub_u32_e32 v28, v167, v41
	v_max3_u32 v24, v26, v27, v28
	v_sub_u32_e32 v29, v171, v41
	v_sub_u32_e32 v30, v176, v41
	v_max3_u32 v24, v24, v29, v30
	v_sub_u32_e32 v31, v179, v41
	v_sub_u32_e32 v32, v184, v41
	v_max3_u32 v24, v24, v31, v32
	v_sub_u32_e32 v33, v187, v41
	v_sub_u32_e32 v26, v183, v41
	v_max3_u32 v24, v24, v33, v26
	v_sub_u32_e32 v27, v182, v41
	v_sub_u32_e32 v28, v162, v41
	v_max3_u32 v24, v24, v27, v28
	v_sub_u32_e32 v29, v164, v41
	v_sub_u32_e32 v30, v87, v41
	v_max3_u32 v24, v24, v29, v30
	v_mov_b32_e32 v25, v24
	s_nop 1
	v_permlane16_swap_b32 v24, v25
	s_nop 1
	v_max_u32_e32 v24, v24, v25
	v_mov_b32_e32 v25, v24
	s_nop 1
	v_permlane32_swap_b32 v24, v25
	s_nop 1
	v_max_u32_e32 v24, v24, v25
	v_add_u32_e32 v42, v24, v41
	v_sub_u32_e32 v26, v86, v42
	v_sub_u32_e32 v27, v88, v42
	v_sub_u32_e32 v28, v167, v42
	v_max3_u32 v24, v26, v27, v28
	v_sub_u32_e32 v29, v171, v42
	v_sub_u32_e32 v30, v176, v42
	v_max3_u32 v24, v24, v29, v30
	v_sub_u32_e32 v31, v179, v42
	v_sub_u32_e32 v32, v184, v42
	v_max3_u32 v24, v24, v31, v32
	v_sub_u32_e32 v33, v187, v42
	v_sub_u32_e32 v26, v183, v42
	v_max3_u32 v24, v24, v33, v26
	v_sub_u32_e32 v27, v182, v42
	v_sub_u32_e32 v28, v162, v42
	v_max3_u32 v24, v24, v27, v28
	v_sub_u32_e32 v29, v164, v42
; DI void peer_topk_wave(const Params& p, int item, unsigned* lds  ) {
;     ...
; #pragma unroll
;   for (int rr = 0; rr < 16; ++rr) {
;     unsigned m = 0;
; #pragma unroll
;     for (int i = 0; i < 13; ++i) m = umax(m, cand[i]);
;     m = umax(m, (unsigned)__shfl_xor((int)m, 16));
;     m = umax(m, (unsigned)__shfl_xor((int)m, 32));
;     w2[rr] = m;
; #pragma unroll
;     for (int i = 0; i < 13; ++i) cand[i] = (cand[i] == m) ? 0u : cand[i];
;   }
	v_sub_u32_e32 v30, v87, v42
	v_max3_u32 v24, v24, v29, v30
	v_mov_b32_e32 v25, v24
	s_nop 1
	v_permlane16_swap_b32 v24, v25
	s_nop 1
	v_max_u32_e32 v24, v24, v25
	v_mov_b32_e32 v25, v24
	s_nop 1
	v_permlane32_swap_b32 v24, v25
	s_nop 1
	v_max_u32_e32 v24, v24, v25
	v_add_u32_e32 v43, v24, v42
	v_sub_u32_e32 v26, v86, v43
	v_sub_u32_e32 v27, v88, v43
	v_sub_u32_e32 v28, v167, v43
	v_max3_u32 v24, v26, v27, v28
	v_sub_u32_e32 v29, v171, v43
	v_sub_u32_e32 v30, v176, v43
	v_max3_u32 v24, v24, v29, v30
	v_sub_u32_e32 v31, v179, v43
	v_sub_u32_e32 v32, v184, v43
	v_max3_u32 v24, v24, v31, v32
	v_sub_u32_e32 v33, v187, v43
	v_sub_u32_e32 v26, v183, v43
	v_max3_u32 v24, v24, v33, v26
	v_sub_u32_e32 v27, v182, v43
	v_sub_u32_e32 v28, v162, v43
	v_max3_u32 v24, v24, v27, v28
	v_sub_u32_e32 v29, v164, v43
	v_sub_u32_e32 v30, v87, v43
	v_max3_u32 v24, v24, v29, v30
	v_mov_b32_e32 v25, v24
	s_nop 1
	v_permlane16_swap_b32 v24, v25
	s_nop 1
	v_max_u32_e32 v24, v24, v25
	v_mov_b32_e32 v25, v24
	s_nop 1
	v_permlane32_swap_b32 v24, v25
	s_nop 1
	v_max_u32_e32 v24, v24, v25
	v_add_u32_e32 v44, v24, v43
	v_sub_u32_e32 v26, v86, v44
	v_sub_u32_e32 v27, v88, v44
	v_sub_u32_e32 v28, v167, v44
	v_max3_u32 v24, v26, v27, v28
	v_sub_u32_e32 v29, v171, v44
	v_sub_u32_e32 v30, v176, v44
	v_max3_u32 v24, v24, v29, v30
	v_sub_u32_e32 v31, v179, v44
	v_sub_u32_e32 v32, v184, v44
	v_max3_u32 v24, v24, v31, v32
	v_sub_u32_e32 v33, v187, v44
	v_sub_u32_e32 v26, v183, v44
	v_max3_u32 v24, v24, v33, v26
	v_sub_u32_e32 v27, v182, v44
	v_sub_u32_e32 v28, v162, v44
	v_max3_u32 v24, v24, v27, v28
	v_sub_u32_e32 v29, v164, v44
	v_sub_u32_e32 v30, v87, v44
	v_max3_u32 v24, v24, v29, v30
	v_mov_b32_e32 v25, v24
	s_nop 1
	v_permlane16_swap_b32 v24, v25
	s_nop 1
	v_max_u32_e32 v24, v24, v25
	v_mov_b32_e32 v25, v24
	s_nop 1
	v_permlane32_swap_b32 v24, v25
	s_nop 1
	v_max_u32_e32 v24, v24, v25
	v_add_u32_e32 v45, v24, v44
	v_sub_u32_e32 v26, v86, v45
	v_sub_u32_e32 v27, v88, v45
	v_sub_u32_e32 v28, v167, v45
	v_max3_u32 v24, v26, v27, v28
	v_sub_u32_e32 v29, v171, v45
	v_sub_u32_e32 v30, v176, v45
	v_max3_u32 v24, v24, v29, v30
	v_sub_u32_e32 v31, v179, v45
	v_sub_u32_e32 v32, v184, v45
	v_max3_u32 v24, v24, v31, v32
	v_sub_u32_e32 v33, v187, v45
	v_sub_u32_e32 v26, v183, v45
	v_max3_u32 v24, v24, v33, v26
	v_sub_u32_e32 v27, v182, v45
	v_sub_u32_e32 v28, v162, v45
	v_max3_u32 v24, v24, v27, v28
	v_sub_u32_e32 v29, v164, v45
	v_sub_u32_e32 v30, v87, v45
	v_max3_u32 v24, v24, v29, v30
	v_mov_b32_e32 v25, v24
	s_nop 1
	v_permlane16_swap_b32 v24, v25
	s_nop 1
	v_max_u32_e32 v24, v24, v25
	v_mov_b32_e32 v25, v24
	s_nop 1
	v_permlane32_swap_b32 v24, v25
	s_nop 1
	v_max_u32_e32 v24, v24, v25
	v_add_u32_e32 v46, v24, v45
	v_sub_u32_e32 v26, v86, v46
	v_sub_u32_e32 v27, v88, v46
	v_sub_u32_e32 v28, v167, v46
	v_max3_u32 v24, v26, v27, v28
	v_sub_u32_e32 v29, v171, v46
	v_sub_u32_e32 v30, v176, v46
	v_max3_u32 v24, v24, v29, v30
	v_sub_u32_e32 v31, v179, v46
	v_sub_u32_e32 v32, v184, v46
	v_max3_u32 v24, v24, v31, v32
	v_sub_u32_e32 v33, v187, v46
	v_sub_u32_e32 v26, v183, v46
	v_max3_u32 v24, v24, v33, v26
	v_sub_u32_e32 v27, v182, v46
	v_sub_u32_e32 v28, v162, v46
	v_max3_u32 v24, v24, v27, v28
	v_sub_u32_e32 v29, v164, v46
	v_sub_u32_e32 v30, v87, v46
	v_max3_u32 v24, v24, v29, v30
	v_mov_b32_e32 v25, v24
	s_nop 1
	v_permlane16_swap_b32 v24, v25
	s_nop 1
	v_max_u32_e32 v24, v24, v25
	v_mov_b32_e32 v25, v24
	s_nop 1
	v_permlane32_swap_b32 v24, v25
	s_nop 1
	v_max_u32_e32 v24, v24, v25
	v_add_u32_e32 v47, v24, v46
	v_sub_u32_e32 v26, v86, v47
	v_sub_u32_e32 v27, v88, v47
	v_sub_u32_e32 v28, v167, v47
	v_max3_u32 v24, v26, v27, v28
	v_sub_u32_e32 v29, v171, v47
	v_sub_u32_e32 v30, v176, v47
	v_max3_u32 v24, v24, v29, v30
	v_sub_u32_e32 v31, v179, v47
	v_sub_u32_e32 v32, v184, v47
	v_max3_u32 v24, v24, v31, v32
	v_sub_u32_e32 v33, v187, v47
	v_sub_u32_e32 v26, v183, v47
	v_max3_u32 v24, v24, v33, v26
	v_sub_u32_e32 v27, v182, v47
	v_sub_u32_e32 v28, v162, v47
	v_max3_u32 v24, v24, v27, v28
	v_sub_u32_e32 v29, v164, v47
	v_sub_u32_e32 v30, v87, v47
	v_max3_u32 v24, v24, v29, v30
	v_mov_b32_e32 v25, v24
	s_nop 1
	v_permlane16_swap_b32 v24, v25
	s_nop 1
	v_max_u32_e32 v24, v24, v25
	v_mov_b32_e32 v25, v24
	s_nop 1
	v_permlane32_swap_b32 v24, v25
	s_nop 1
	v_max_u32_e32 v24, v24, v25
	v_add_u32_e32 v48, v24, v47
	v_sub_u32_e32 v26, v86, v48
	v_sub_u32_e32 v27, v88, v48
	v_sub_u32_e32 v28, v167, v48
	v_max3_u32 v24, v26, v27, v28
	v_sub_u32_e32 v29, v171, v48
	v_sub_u32_e32 v30, v176, v48
	v_max3_u32 v24, v24, v29, v30
	v_sub_u32_e32 v31, v179, v48
	v_sub_u32_e32 v32, v184, v48
	v_max3_u32 v24, v24, v31, v32
	v_sub_u32_e32 v33, v187, v48
	v_sub_u32_e32 v26, v183, v48
	v_max3_u32 v24, v24, v33, v26
	v_sub_u32_e32 v27, v182, v48
	v_sub_u32_e32 v28, v162, v48
	v_max3_u32 v24, v24, v27, v28
	v_sub_u32_e32 v29, v164, v48
	v_sub_u32_e32 v30, v87, v48
	v_max3_u32 v24, v24, v29, v30
	v_mov_b32_e32 v25, v24
	s_nop 1
	v_permlane16_swap_b32 v24, v25
	s_nop 1
	v_max_u32_e32 v24, v24, v25
	v_mov_b32_e32 v25, v24
	s_nop 1
	v_permlane32_swap_b32 v24, v25
	s_nop 1
	v_max_u32_e32 v24, v24, v25
	v_add_u32_e32 v49, v24, v48
	v_sub_u32_e32 v26, v86, v49
	v_sub_u32_e32 v27, v88, v49
	v_sub_u32_e32 v28, v167, v49
	v_max3_u32 v24, v26, v27, v28
	v_sub_u32_e32 v29, v171, v49
	v_sub_u32_e32 v30, v176, v49
	v_max3_u32 v24, v24, v29, v30
	v_sub_u32_e32 v31, v179, v49
	v_sub_u32_e32 v32, v184, v49
	v_max3_u32 v24, v24, v31, v32
	v_sub_u32_e32 v33, v187, v49
	v_sub_u32_e32 v26, v183, v49
	v_max3_u32 v24, v24, v33, v26
	v_sub_u32_e32 v27, v182, v49
	v_sub_u32_e32 v28, v162, v49
	v_max3_u32 v24, v24, v27, v28
; DI void peer_topk_wave(const Params& p, int item, unsigned* lds  ) {
;     ...
; #pragma unroll
;   for (int rr = 0; rr < 16; ++rr) {
;     unsigned m = 0;
; #pragma unroll
;     for (int i = 0; i < 13; ++i) m = umax(m, cand[i]);
;     m = umax(m, (unsigned)__shfl_xor((int)m, 16));
;     m = umax(m, (unsigned)__shfl_xor((int)m, 32));
;     w2[rr] = m;
; #pragma unroll
;     for (int i = 0; i < 13; ++i) cand[i] = (cand[i] == m) ? 0u : cand[i];
;   }
;   if (kg == 0) {
; #pragma unroll
;     for (int i = 0; i < 16; ++i) { lds[r * 32 + i] = win[0][i] & 127u; lds[r * 32 + 16 + i] = win[1][i] & 127u; }
;   }
	v_sub_u32_e32 v29, v164, v49
	v_sub_u32_e32 v30, v87, v49
	v_max3_u32 v24, v24, v29, v30
	v_mov_b32_e32 v25, v24
	s_nop 1
	v_permlane16_swap_b32 v24, v25
	s_nop 1
	v_max_u32_e32 v24, v24, v25
	v_mov_b32_e32 v25, v24
	s_nop 1
	v_permlane32_swap_b32 v24, v25
	s_nop 1
	v_max_u32_e32 v24, v24, v25
	v_add_u32_e32 v50, v24, v49
	v_sub_u32_e32 v26, v86, v50
	v_sub_u32_e32 v27, v88, v50
	v_sub_u32_e32 v28, v167, v50
	v_max3_u32 v24, v26, v27, v28
	v_sub_u32_e32 v29, v171, v50
	v_sub_u32_e32 v30, v176, v50
	v_max3_u32 v24, v24, v29, v30
	v_sub_u32_e32 v31, v179, v50
	v_sub_u32_e32 v32, v184, v50
	v_max3_u32 v24, v24, v31, v32
	v_sub_u32_e32 v33, v187, v50
	v_sub_u32_e32 v26, v183, v50
	v_max3_u32 v24, v24, v33, v26
	v_sub_u32_e32 v27, v182, v50
	v_sub_u32_e32 v28, v162, v50
	v_max3_u32 v24, v24, v27, v28
	v_sub_u32_e32 v29, v164, v50
	v_sub_u32_e32 v30, v87, v50
	v_max3_u32 v24, v24, v29, v30
	v_mov_b32_e32 v25, v24
	s_nop 1
	v_permlane16_swap_b32 v24, v25
	s_nop 1
	v_max_u32_e32 v24, v24, v25
	v_mov_b32_e32 v25, v24
	s_nop 1
	v_permlane32_swap_b32 v24, v25
	s_nop 1
	v_max_u32_e32 v24, v24, v25
	v_add_u32_e32 v51, v24, v50
	v_sub_u32_e32 v26, v86, v51
	v_sub_u32_e32 v27, v88, v51
	v_sub_u32_e32 v28, v167, v51
	v_max3_u32 v24, v26, v27, v28
	v_sub_u32_e32 v29, v171, v51
	v_sub_u32_e32 v30, v176, v51
	v_max3_u32 v24, v24, v29, v30
	v_sub_u32_e32 v31, v179, v51
	v_sub_u32_e32 v32, v184, v51
	v_max3_u32 v24, v24, v31, v32
	v_sub_u32_e32 v33, v187, v51
	v_sub_u32_e32 v26, v183, v51
	v_max3_u32 v24, v24, v33, v26
	v_sub_u32_e32 v27, v182, v51
	v_sub_u32_e32 v28, v162, v51
	v_max3_u32 v24, v24, v27, v28
	v_sub_u32_e32 v29, v164, v51
	v_sub_u32_e32 v30, v87, v51
	v_max3_u32 v24, v24, v29, v30
	v_mov_b32_e32 v25, v24
	s_nop 1
	v_permlane16_swap_b32 v24, v25
	s_nop 1
	v_max_u32_e32 v24, v24, v25
	v_mov_b32_e32 v25, v24
	s_nop 1
	v_permlane32_swap_b32 v24, v25
	s_nop 1
	v_max_u32_e32 v24, v24, v25
	v_add_u32_e32 v52, v24, v51
	v_sub_u32_e32 v26, v86, v52
	v_sub_u32_e32 v27, v88, v52
	v_sub_u32_e32 v28, v167, v52
	v_max3_u32 v24, v26, v27, v28
	v_sub_u32_e32 v29, v171, v52
	v_sub_u32_e32 v30, v176, v52
	v_max3_u32 v24, v24, v29, v30
	v_sub_u32_e32 v31, v179, v52
	v_sub_u32_e32 v32, v184, v52
	v_max3_u32 v24, v24, v31, v32
	v_sub_u32_e32 v33, v187, v52
	v_sub_u32_e32 v26, v183, v52
	v_max3_u32 v24, v24, v33, v26
	v_sub_u32_e32 v27, v182, v52
	v_sub_u32_e32 v28, v162, v52
	v_max3_u32 v24, v24, v27, v28
	v_sub_u32_e32 v29, v164, v52
	v_sub_u32_e32 v30, v87, v52
	v_max3_u32 v24, v24, v29, v30
	v_mov_b32_e32 v25, v24
	s_nop 1
	v_permlane16_swap_b32 v24, v25
	s_nop 1
	v_max_u32_e32 v24, v24, v25
	v_mov_b32_e32 v25, v24
	s_nop 1
	v_permlane32_swap_b32 v24, v25
	s_nop 1
	v_max_u32_e32 v24, v24, v25
	v_add_u32_e32 v53, v24, v52
	v_sub_u32_e32 v26, v86, v53
	v_sub_u32_e32 v27, v88, v53
	v_sub_u32_e32 v28, v167, v53
	v_max3_u32 v24, v26, v27, v28
	v_sub_u32_e32 v29, v171, v53
	v_sub_u32_e32 v30, v176, v53
	v_max3_u32 v24, v24, v29, v30
	v_sub_u32_e32 v31, v179, v53
	v_sub_u32_e32 v32, v184, v53
	v_max3_u32 v24, v24, v31, v32
	v_sub_u32_e32 v33, v187, v53
	v_sub_u32_e32 v26, v183, v53
	v_max3_u32 v24, v24, v33, v26
	v_sub_u32_e32 v27, v182, v53
	v_sub_u32_e32 v28, v162, v53
	v_max3_u32 v24, v24, v27, v28
	v_sub_u32_e32 v29, v164, v53
	v_sub_u32_e32 v30, v87, v53
	v_max3_u32 v24, v24, v29, v30
	v_mov_b32_e32 v25, v24
	s_nop 1
	v_permlane16_swap_b32 v24, v25
	s_nop 1
	v_max_u32_e32 v24, v24, v25
	v_mov_b32_e32 v25, v24
	s_nop 1
	v_permlane32_swap_b32 v24, v25
	s_nop 1
	v_max_u32_e32 v24, v24, v25
	v_add_u32_e32 v54, v24, v53
	v_sub_u32_e32 v26, v86, v54
	v_sub_u32_e32 v27, v88, v54
	v_sub_u32_e32 v28, v167, v54
	v_max3_u32 v24, v26, v27, v28
	v_sub_u32_e32 v29, v171, v54
	v_sub_u32_e32 v30, v176, v54
	v_max3_u32 v24, v24, v29, v30
	v_sub_u32_e32 v31, v179, v54
	v_sub_u32_e32 v32, v184, v54
	v_max3_u32 v24, v24, v31, v32
	v_sub_u32_e32 v33, v187, v54
	v_sub_u32_e32 v26, v183, v54
	v_max3_u32 v24, v24, v33, v26
	v_sub_u32_e32 v27, v182, v54
	v_sub_u32_e32 v28, v162, v54
	v_max3_u32 v24, v24, v27, v28
	v_sub_u32_e32 v29, v164, v54
	v_sub_u32_e32 v30, v87, v54
	v_max3_u32 v24, v24, v29, v30
	v_mov_b32_e32 v25, v24
	s_nop 1
	v_permlane16_swap_b32 v24, v25
	s_nop 1
	v_max_u32_e32 v24, v24, v25
	v_mov_b32_e32 v25, v24
	s_nop 1
	v_permlane32_swap_b32 v24, v25
	s_nop 1
	v_max_u32_e32 v24, v24, v25
	v_add_u32_e32 v55, v24, v54
	v_mov_b32_e32 v166, v40
	v_mov_b32_e32 v88, v41
	v_mov_b32_e32 v87, v42
	v_mov_b32_e32 v86, v43
	v_mov_b32_e32 v169, v44
	v_mov_b32_e32 v164, v45
	v_mov_b32_e32 v162, v46
	v_mov_b32_e32 v89, v47
	v_mov_b32_e32 v172, v48
	v_mov_b32_e32 v168, v49
	v_mov_b32_e32 v167, v50
	v_mov_b32_e32 v165, v51
	v_mov_b32_e32 v176, v52
	v_mov_b32_e32 v173, v53
	v_mov_b32_e32 v171, v54
	v_mov_b32_e32 v177, v55
	ds_bpermute_b32 v178, v112, v177
	s_and_saveexec_b64 s[0:1], s[6:7]
	s_cbranch_execz .LBB0_1281
	v_and_b32_e32 v181, 0x7f, v147
	v_and_b32_e32 v180, 0x7f, v16
	v_and_b32_e32 v1, 0x7f, v1
	v_and_b32_e32 v0, 0x7f, v0
	v_and_b32_e32 v183, 0x7f, v149
	v_and_b32_e32 v182, 0x7f, v148
	v_and_b32_e32 v3, 0x7f, v3
	v_and_b32_e32 v2, 0x7f, v2
	ds_write_b128 v110, v[180:183]
	ds_write_b128 v110, v[0:3] offset:64
	v_and_b32_e32 v1, 0x7f, v151
	v_and_b32_e32 v0, 0x7f, v150
	v_and_b32_e32 v3, 0x7f, v153
	v_and_b32_e32 v2, 0x7f, v152
	v_and_b32_e32 v5, 0x7f, v5
	v_and_b32_e32 v4, 0x7f, v4
	v_and_b32_e32 v7, 0x7f, v7
	v_and_b32_e32 v6, 0x7f, v6
	ds_write_b128 v110, v[0:3] offset:16
	ds_write_b128 v110, v[4:7] offset:80
	v_and_b32_e32 v1, 0x7f, v155
	v_and_b32_e32 v0, 0x7f, v154
	v_and_b32_e32 v3, 0x7f, v157
	v_and_b32_e32 v2, 0x7f, v156
	v_and_b32_e32 v5, 0x7f, v9
	v_and_b32_e32 v4, 0x7f, v8
	v_and_b32_e32 v7, 0x7f, v11
	v_and_b32_e32 v6, 0x7f, v10
	ds_write_b128 v110, v[0:3] offset:32
	ds_write_b128 v110, v[4:7] offset:96
	v_and_b32_e32 v1, 0x7f, v159
	v_and_b32_e32 v0, 0x7f, v158
	v_and_b32_e32 v3, 0x7f, v161
	v_and_b32_e32 v2, 0x7f, v160
	v_and_b32_e32 v5, 0x7f, v13
	v_and_b32_e32 v4, 0x7f, v12
	v_and_b32_e32 v7, 0x7f, v15
	v_and_b32_e32 v6, 0x7f, v14
	ds_write_b128 v110, v[0:3] offset:48
	ds_write_b128 v110, v[4:7] offset:112
